# ret_state: lanes holding the other dv half skip their V loads, V scaling and V LDS writes (exec mask)
# baseline (speedup 1.0000x reference)
; __device__ __forceinline__ int v_st(int k, int c) { const int kk = (k & ~0xC) | ((k & 4) << 1) | ((k & 8) >> 1); return ((kk >> 3) * 4 + (c >> 5)) * 512 + ((kk & 7) * 32 + (c & 31)) * 2; }
; __device__ __forceinline__ int v_rd_base(int lane) { return ((lane & 3) << 3) | (((lane >> 2) & 3) << 6) | (((lane >> 4) & 1) << 5) | (((lane >> 5) & 1) << 8); }
; __device__ __forceinline__ void ret_state_unit(const bf16_t* __restrict__ Kh, const bf16_t* __restrict__ Vh, bf16_t* ST  , int dir, int hf  , float l2, char* lds) {
;   int tid_ = threadIdx.x; asm volatile("" : "+v"(tid_));
;   const int tid = tid_, wid = tid >> 6, lane = tid & 63, r32 = lane & 31, hi = lane >> 5, d0k = wid & 3, dvp = wid >> 2;
;   constexpr int SHV = KVBLK * 128 * 2; char* K_lds = lds; char* V_lds = lds + 2 * SHV;
;   const int sr = tid >> 4, sc = (tid & 15) * 8, vst0 = v_st(sr, sc), vst1 = v_st(32 + sr, sc);
;   const float w0 = dir ? __builtin_amdgcn_exp2f(l2 * (float)sr) : __builtin_amdgcn_exp2f(l2 * (float)(63 - sr)), w1 = dir ? __builtin_amdgcn_exp2f(l2 * (float)(32 + sr)) : __builtin_amdgcn_exp2f(l2 * (float)(31 - sr));
;   const float dec64 = __builtin_amdgcn_exp2f(64.f * l2);
;   const int kb = (int)(uintptr_t)K_lds + v_rd_base(lane) + d0k * 512, vb = (int)(uintptr_t)V_lds + v_rd_base(lane) + (2 * hf + dvp) * 512;
; template <int ph> __device__ __forceinline__ void run_phase(const MArgs& a, unsigned char* lds, int tid, int lane, int wave, int G, int bx, int vcu) {
;     ...
;     { const int bh = vcu >> 2, dir = (vcu >> 1) & 1, hf = vcu & 1, b = bh >> 2, h = bh & 3; const float dl = a.in[24][dir * 4 + h];
;       const float l2 = __uint_as_float(__builtin_amdgcn_readfirstlane(__float_as_uint(-log1pf(expf(-dl)) * LOG2E)));
;       att::ret_state_unit(RK + (size_t)b * RB * 512 + 128 * h, RV + (size_t)b * RB * 512 + 128 * h, (bf16_t*)(ws + R_ST) + (size_t)(bh * 2 + dir) * 8 * 16384, dir, hf, l2, (char*)lds); }
.LBB0_1866:
	s_cmp_gt_i32 s94, 14
	s_cselect_b64 s[0:1], -1, 0
	s_cmp_lt_i32 s95, 15
	s_cselect_b64 s[4:5], -1, 0
	s_or_b64 s[0:1], s[0:1], s[4:5]
	s_and_b64 vcc, exec, s[0:1]
	s_cbranch_vccnz .LBB0_2021
	s_mov_b32 s36, 0x00ff00ff
	s_bitcmp1_b32 s92, 0
	s_cselect_b32 s36, 0xff00ff00, s36
	s_mov_b32 s37, s36
	s_add_u32 s3, s26, 0x12700000
	s_addc_u32 s31, s27, 0
	s_add_u32 s66, s26, 0x14b00000
	s_addc_u32 s67, s27, 0
	s_ashr_i32 s0, s92, 2
	s_bfe_u32 s4, s92, 0x10001
	s_and_b32 s1, s0, 3
	s_lshl_b32 s5, s4, 4
	s_lshl_b32 s6, s1, 2
	s_or_b32 s5, s5, s6
	s_waitcnt lgkmcnt(0)
	v_mov_b32_e32 v1, s5
	global_load_dword v1, v1, s[76:77]
	s_mov_b32 s14, 0xbfb8aa3b
	s_mov_b32 s11, 0x42ce8ed0
	s_mov_b32 s15, 0xc2b17218
	v_mov_b32_e32 v2, 0x7f800000
	s_mov_b32 s16, 0x3f2aaaab
	v_mov_b32_e32 v5, 0x3ecc95a3
	v_mov_b32_e32 v4, 0x3f317218
	s_mov_b32 s17, 0x3f317218
	s_ashr_i32 s6, s92, 4
	s_bfe_i32 s13, s92, 0x10001
	s_mul_i32 s9, s6, 0x240000
	s_mul_hi_i32 s8, s6, 0x240000
	s_add_u32 s6, s3, s9
	s_addc_u32 s7, s31, s8
	s_lshl_b32 s1, s1, 8
	s_add_u32 s6, s6, s1
	s_addc_u32 s7, s7, 0
	s_add_u32 s9, s66, s9
	s_addc_u32 s18, s67, s8
	s_add_u32 s8, s9, s1
	s_addc_u32 s9, s18, 0
	s_add_u32 s30, s26, 0x1b700000
	s_addc_u32 s34, s27, 0
	s_lshl_b32 s0, s0, 1
	s_or_b32 s0, s0, s4
	s_ashr_i32 s1, s0, 31
	s_mov_b32 s10, 0x7f800000
	s_lshl_b64 s[0:1], s[0:1], 18
	s_waitcnt vmcnt(0)
	v_mov_b32_e32 v20, v0
	s_mov_b32 s5, 0
	v_ashrrev_i32_e32 v66, 4, v20
	v_ashrrev_i32_e32 v67, 31, v66
	v_lshl_add_u64 v[70:71], v[66:67], 0, 32
	s_mov_b32 s12, 0x33800000
	v_mov_b32_e32 v3, 0
	v_and_b32_e32 v21, 31, v20
	s_mov_b32 s18, 36
	s_movk_i32 s19, 0x1000
	s_mov_b32 s21, 0
	v_mov_b32_e32 v26, v3
	v_mov_b32_e32 v27, v3
	v_mov_b32_e32 v28, v3
	v_mov_b32_e32 v29, v3
	v_mov_b32_e32 v30, v3
	v_mov_b32_e32 v31, v3
	v_mov_b32_e32 v32, v3
	v_mov_b32_e32 v33, v3
	v_mul_f32_e32 v6, 0xbfb8aa3b, v1
	v_fma_f32 v7, v1, s14, -v6
	v_rndne_f32_e32 v8, v6
	v_fmamk_f32 v7, v1, 0xb2a5705f, v7
	v_sub_f32_e32 v6, v6, v8
	v_add_f32_e32 v6, v6, v7
	v_cvt_i32_f32_e32 v8, v8
	v_exp_f32_e32 v6, v6
	v_cmp_nlt_f32_e32 vcc, s11, v1
	v_ldexp_f32 v6, v6, v8
	s_nop 0
	v_cndmask_b32_e32 v6, 0, v6, vcc
	v_cmp_ngt_f32_e32 vcc, s15, v1
	s_nop 1
	v_cndmask_b32_e32 v1, v2, v6, vcc
	v_add_f32_e32 v8, 1.0, v1
	v_add_f32_e32 v9, -1.0, v8
	v_frexp_mant_f32_e32 v10, v8
	v_cvt_f64_f32_e32 v[6:7], v8
	v_sub_f32_e32 v11, v9, v8
	v_frexp_exp_i32_f64_e32 v6, v[6:7]
	v_cmp_gt_f32_e32 vcc, s16, v10
	v_sub_f32_e32 v9, v1, v9
	v_add_f32_e32 v7, 1.0, v11
	v_subbrev_co_u32_e32 v6, vcc, 0, v6, vcc
	v_add_f32_e32 v7, v9, v7
	v_sub_u32_e32 v9, 0, v6
	v_ldexp_f32 v8, v8, v9
	v_add_f32_e32 v10, -1.0, v8
	v_add_f32_e32 v11, 1.0, v8
	v_ldexp_f32 v7, v7, v9
	v_add_f32_e32 v9, 1.0, v10
	v_add_f32_e32 v12, -1.0, v11
	v_sub_f32_e32 v9, v8, v9
	v_sub_f32_e32 v8, v8, v12
	v_add_f32_e32 v12, v7, v9
	v_add_f32_e32 v7, v7, v8
	v_add_f32_e32 v14, v11, v7
	v_rcp_f32_e32 v15, v14
	v_add_f32_e32 v9, v10, v12
	v_sub_f32_e32 v10, v10, v9
	v_sub_f32_e32 v8, v11, v14
	v_mul_f32_e32 v17, v9, v15
	v_add_f32_e32 v16, v12, v10
	v_mul_f32_e32 v10, v14, v17
	v_add_f32_e32 v7, v7, v8
	v_fma_f32 v12, v17, v14, -v10
	v_fmac_f32_e32 v12, v17, v7
	v_add_f32_e32 v8, v10, v12
	v_sub_f32_e32 v11, v9, v8
	v_mov_b32_e32 v13, v8
	v_pk_add_f32 v[8:9], v[8:9], v[10:11] neg_lo:[0,1] neg_hi:[0,1]
	v_cvt_f32_i32_e32 v6, v6
	v_pk_add_f32 v[8:9], v[8:9], v[12:13] neg_lo:[0,1] neg_hi:[0,1]
	v_cmp_neq_f32_e32 vcc, s10, v1
	v_add_f32_e32 v9, v16, v9
	v_add_f32_e32 v8, v8, v9
	v_add_f32_e32 v9, v11, v8
	v_mul_f32_e32 v13, v15, v9
	v_mul_f32_e32 v10, v14, v13
	v_sub_f32_e32 v11, v11, v9
	v_add_f32_e32 v18, v17, v13
	v_fma_f32 v12, v13, v14, -v10
	v_add_f32_e32 v16, v8, v11
	v_sub_f32_e32 v8, v18, v17
	v_fmac_f32_e32 v12, v13, v7
	v_sub_f32_e32 v7, v13, v8
	v_add_f32_e32 v8, v10, v12
	v_sub_f32_e32 v11, v9, v8
	v_mov_b32_e32 v13, v8
	v_pk_add_f32 v[8:9], v[8:9], v[10:11] neg_lo:[0,1] neg_hi:[0,1]
	s_add_u32 s10, s30, s0
	v_pk_add_f32 v[8:9], v[8:9], v[12:13] neg_lo:[0,1] neg_hi:[0,1]
	s_addc_u32 s11, s34, s1
	v_add_f32_e32 v9, v16, v9
	v_add_f32_e32 v8, v8, v9
	v_add_f32_e32 v8, v11, v8
	v_mul_f32_e32 v8, v15, v8
	v_add_f32_e32 v7, v7, v8
	v_add_f32_e32 v8, v18, v7
	v_mul_f32_e32 v10, v8, v8
	v_sub_f32_e32 v11, v8, v18
	v_fmac_f32_e32 v5, 0x3e9b6dac, v10
	v_sub_f32_e32 v11, v7, v11
	v_mul_f32_e32 v7, v8, v10
	v_fmaak_f32 v5, v10, v5, 0x3f2aaada
	v_pk_mul_f32 v[4:5], v[6:7], v[4:5]
	v_ldexp_f32 v9, v8, 1
	v_fma_f32 v7, v6, s17, -v4
	v_fmamk_f32 v8, v6, 0xb102e308, v7
	v_pk_add_f32 v[6:7], v[4:5], v[8:9]
	v_ldexp_f32 v11, v11, 1
	v_sub_f32_e32 v14, v7, v9
	v_pk_add_f32 v[12:13], v[6:7], v[4:5] neg_lo:[0,1] neg_hi:[0,1]
	v_sub_f32_e32 v5, v5, v14
	v_mov_b32_e32 v10, v4
	v_add_f32_e32 v11, v11, v5
	v_pk_add_f32 v[16:17], v[6:7], v[10:11]
	v_mov_b32_e32 v9, v6
	v_mov_b32_e32 v13, v17
	v_pk_add_f32 v[18:19], v[8:9], v[12:13] neg_lo:[0,1] neg_hi:[0,1]
	v_pk_add_f32 v[8:9], v[8:9], v[12:13]
	v_mov_b32_e32 v4, v7
	v_mov_b32_e32 v15, v6
	v_pk_add_f32 v[6:7], v[8:9], v[6:7] op_sel:[1,0] op_sel_hi:[0,1] neg_lo:[0,1] neg_hi:[0,1]
	v_mov_b32_e32 v14, v11
	v_mov_b32_e32 v10, v17
	v_mov_b32_e32 v11, v9
	v_mov_b32_e32 v5, v6
	v_pk_add_f32 v[12:13], v[16:17], v[6:7] op_sel_hi:[1,0] neg_lo:[0,1] neg_hi:[0,1]
	v_pk_add_f32 v[4:5], v[10:11], v[4:5] neg_lo:[0,1] neg_hi:[0,1]
	v_mov_b32_e32 v12, v18
	v_pk_add_f32 v[4:5], v[14:15], v[4:5] neg_lo:[0,1] neg_hi:[0,1]
	v_mov_b32_e32 v19, v9
	v_pk_add_f32 v[6:7], v[12:13], v[4:5]
	s_cmp_eq_u32 s4, 0
	v_pk_add_f32 v[10:11], v[6:7], v[6:7] op_sel:[0,1] op_sel_hi:[1,0]
	s_cselect_b64 s[0:1], -1, 0
	v_pk_add_f32 v[8:9], v[8:9], v[10:11] op_sel:[1,0] op_sel_hi:[0,1]
; __device__ __forceinline__ int v_rd_base(int lane) { return ((lane & 3) << 3) | (((lane >> 2) & 3) << 6) | (((lane >> 4) & 1) << 5) | (((lane >> 5) & 1) << 8); }
; #define RS_LOAD(S, s) do { const long k0 = 64L * RS_TILE(s); ks0##S = *reinterpret_cast<const bf16x8*>(&Kh[(k0 + sr) * 512 + sc]); ks1##S = *reinterpret_cast<const bf16x8*>(&Kh[(k0 + 32 + sr) * 512 + sc]); \
;     vs0##S = *reinterpret_cast<const bf16x8*>(&Vh[(k0 + sr) * 512 + sc]); vs1##S = *reinterpret_cast<const bf16x8*>(&Vh[(k0 + 32 + sr) * 512 + sc]); } while (0)
; #define RS_WRITE(b, S) do { *(bf16x8*)(K_lds + (b) * SHV + vst0) = ks0##S; *(bf16x8*)(K_lds + (b) * SHV + vst1) = ks1##S; RS_SCALE(vs0##S, w0); RS_SCALE(vs1##S, w1); \
;     *(bf16x8*)(V_lds + (b) * SHV + vst0) = vs0##S; *(bf16x8*)(V_lds + (b) * SHV + vst1) = vs1##S; } while (0)
; #define RS_LBAR() do { asm volatile("s_waitcnt lgkmcnt(0)" ::: "memory"); __builtin_amdgcn_s_barrier(); asm volatile("" ::: "memory"); } while (0)
; __device__ __forceinline__ void ret_state_unit(const bf16_t* __restrict__ Kh, const bf16_t* __restrict__ Vh, bf16_t* ST  , int dir, int hf  , float l2, char* lds) {
;     ...
;   const float w0 = dir ? __builtin_amdgcn_exp2f(l2 * (float)sr) : __builtin_amdgcn_exp2f(l2 * (float)(63 - sr)), w1 = dir ? __builtin_amdgcn_exp2f(l2 * (float)(32 + sr)) : __builtin_amdgcn_exp2f(l2 * (float)(31 - sr));
;   const float dec64 = __builtin_amdgcn_exp2f(64.f * l2);
;   const int kb = (int)(uintptr_t)K_lds + v_rd_base(lane) + d0k * 512, vb = (int)(uintptr_t)V_lds + v_rd_base(lane) + (2 * hf + dvp) * 512;
;   f32x16 o0 = {}, o1 = {};
;   bf16x8 ks0A, ks1A, vs0A, vs1A, ks0B, ks1B, vs0B, vs1B;
;     ...
;   RS_LOAD(A, 0); RS_LOAD(B, 1); asm volatile("s_waitcnt vmcnt(4)" ::: "memory"); RS_WRITE(0, A); RS_LBAR();
	v_mov_b32_e32 v7, v8
	v_mov_b32_e32 v5, v10
	v_pk_add_f32 v[10:11], v[6:7], v[18:19] neg_lo:[0,1] neg_hi:[0,1]
	s_and_b64 s[14:15], s[0:1], exec
	v_sub_f32_e32 v6, v6, v10
	v_pk_add_f32 v[4:5], v[4:5], v[10:11] neg_lo:[0,1] neg_hi:[0,1]
	v_sub_f32_e32 v6, v18, v6
	v_add_f32_e32 v4, v4, v6
	v_add_f32_e32 v4, v4, v5
	v_add_f32_e32 v4, v8, v4
	v_cndmask_b32_e32 v2, v2, v4, vcc
	v_lshlrev_b32_e32 v12, 3, v20
	v_sub_u32_e32 v4, 63, v66
	s_cselect_b32 s4, 64, 0x80
	s_and_b32 s14, s13, 0xc0
	s_mov_b32 s15, s5
	v_and_b32_e32 v68, 0x78, v12
	v_cndmask_b32_e64 v13, v66, v4, s[0:1]
	v_lshl_add_u64 v[4:5], s[14:15], 0, v[66:67]
	v_lshl_add_u64 v[8:9], v[70:71], 0, s[14:15]
	v_lshlrev_b64 v[4:5], 10, v[4:5]
	v_lshlrev_b32_e32 v18, 1, v68
	v_lshlrev_b64 v[8:9], 10, v[8:9]
	v_or_b32_e32 v4, v4, v18
	v_or_b32_e32 v8, v8, v18
	v_lshl_add_u64 v[6:7], s[6:7], 0, v[4:5]
	v_lshl_add_u64 v[10:11], s[6:7], 0, v[8:9]
	global_load_dwordx4 v[34:37], v[6:7], off
	global_load_dwordx4 v[38:41], v[10:11], off
	v_and_b32_e32 v10, 0xfffff0, v66
	v_lshlrev_b32_e32 v11, 1, v66
	v_and_or_b32 v10, v11, 8, v10
	v_lshrrev_b32_e32 v15, 1, v66
	v_lshrrev_b32_e32 v10, 1, v10
	v_bfe_u32 v16, v12, 5, 2
	v_and_b32_e32 v19, 3, v66
	v_or_b32_e32 v17, v10, v16
	v_and_or_b32 v15, v15, 4, v19
	v_lshlrev_b32_e32 v19, 4, v20
	v_lshlrev_b32_e32 v17, 9, v17
	v_lshlrev_b32_e32 v15, 6, v15
	v_and_b32_e32 v22, 48, v19
	v_or3_b32 v23, v17, v15, v22
	v_add_u32_e32 v17, 32, v66
	v_and_b32_e32 v24, 0xfffff0, v17
	v_lshlrev_b32_e32 v25, 1, v17
	v_and_or_b32 v24, v25, 8, v24
	v_lshl_add_u64 v[4:5], s[8:9], 0, v[4:5]
	v_lshrrev_b32_e32 v24, 1, v24
	global_load_dwordx4 v[4:7], v[4:5], off
	v_or_b32_e32 v16, v24, v16
	v_sub_u32_e32 v24, 31, v66
	v_cmp_lt_f32_e64 vcc, |v1|, s12
	v_cvt_f32_i32_e32 v13, v13
	v_cndmask_b32_e64 v17, v17, v24, s[0:1]
	v_cndmask_b32_e32 v1, v2, v1, vcc
	v_cvt_f32_i32_e32 v17, v17
	v_readfirstlane_b32 s12, v1
	v_mov_b32_e32 v1, 0xbfb8aa3b
	v_lshl_add_u64 v[8:9], s[8:9], 0, v[8:9]
	v_mul_f32_e32 v1, s12, v1
	v_mul_f32_e32 v13, v1, v13
	global_load_dwordx4 v[8:11], v[8:9], off
	v_exp_f32_e32 v72, v13
	v_mul_f32_e32 v13, v1, v17
	v_mul_f32_e32 v1, 0x42800000, v1
	v_exp_f32_e32 v74, v13
	v_exp_f32_e32 v76, v1
	v_and_b32_e32 v1, 0xc0, v19
	v_lshlrev_b32_e32 v13, 1, v20
	v_bfe_u32 v2, v20, 6, 2
	v_and_or_b32 v1, v12, 24, v1
	v_and_b32_e32 v13, 32, v13
	v_and_b32_e32 v12, 0x100, v12
	s_cmp_lg_u32 0, -1
	v_or3_b32 v12, v1, v13, v12
	v_lshlrev_b32_e32 v1, 9, v2
	s_cselect_b32 s12, 0, 0
	v_add3_u32 v1, v1, s12, v12
	s_lshl_b32 s12, s92, 1
	v_ashrrev_i32_e32 v14, 8, v20
	s_and_b32 s12, s12, 2
	v_add_u32_e32 v24, s12, v14
	s_add_i32 s12, 0, 0x8000
	s_cmp_lg_u32 s12, -1
	v_lshlrev_b32_e32 v13, 9, v24
	s_cselect_b32 s12, s12, 0
	v_lshlrev_b32_e32 v16, 9, v16
	v_add3_u32 v69, v13, s12, v12
	v_lshl_add_u64 v[12:13], s[4:5], 0, v[66:67]
	v_or3_b32 v22, v16, v15, v22
	v_lshlrev_b64 v[12:13], 10, v[12:13]
	v_lshl_add_u64 v[16:17], v[70:71], 0, s[4:5]
	v_or_b32_e32 v12, v12, v18
	v_lshlrev_b64 v[16:17], 10, v[16:17]
	v_lshl_add_u64 v[14:15], s[6:7], 0, v[12:13]
	v_or_b32_e32 v16, v16, v18
	v_lshl_add_u64 v[12:13], s[8:9], 0, v[12:13]
	v_lshl_add_u64 v[18:19], s[6:7], 0, v[16:17]
	global_load_dwordx4 v[42:45], v[14:15], off
	global_load_dwordx4 v[46:49], v[18:19], off
	v_lshl_add_u64 v[14:15], s[8:9], 0, v[16:17]
	global_load_dwordx4 v[50:53], v[12:13], off
	global_load_dwordx4 v[54:57], v[14:15], off
	v_mov_b32_e32 v73, v72
	v_mov_b32_e32 v75, v74
	v_lshlrev_b32_e32 v2, 13, v2
	v_add_u32_e32 v82, 0, v23
	v_add_u32_e32 v83, 0, v22
	s_waitcnt vmcnt(4)
	s_waitcnt vmcnt(7)
	ds_write_b128 v82, v[34:37]
	s_waitcnt vmcnt(6)
	ds_write_b128 v83, v[38:41]
	v_add_u32_e32 v84, 0x4000, v1
	v_add_u32_e32 v85, 0x4000, v69
	v_mov_b32_e32 v80, v76
	v_mov_b32_e32 v81, v76
	v_mov_b32_e32 v14, v3
	v_mov_b32_e32 v15, v3
	v_mov_b32_e32 v16, v3
	v_mov_b32_e32 v17, v3
	v_mov_b32_e32 v18, v3
	v_mov_b32_e32 v19, v3
	v_mov_b32_e32 v22, v3
	v_mov_b32_e32 v23, v3
	v_mov_b32_e32 v25, v3
	s_waitcnt vmcnt(5)
	v_lshlrev_b32_e32 v12, 16, v4
	v_and_b32_e32 v13, 0xffff0000, v4
	v_lshlrev_b32_e32 v4, 16, v5
	v_and_b32_e32 v5, 0xffff0000, v5
	v_pk_mul_f32 v[4:5], v[72:73], v[4:5] op_sel_hi:[0,1]
	v_cvt_pk_bf16_f32 v59, v4, v5
	v_lshlrev_b32_e32 v4, 16, v6
	v_and_b32_e32 v5, 0xffff0000, v6
	v_pk_mul_f32 v[4:5], v[72:73], v[4:5] op_sel_hi:[0,1]
	v_cvt_pk_bf16_f32 v60, v4, v5
	v_lshlrev_b32_e32 v4, 16, v7
	v_and_b32_e32 v5, 0xffff0000, v7
	v_pk_mul_f32 v[4:5], v[72:73], v[4:5] op_sel_hi:[0,1]
	v_cvt_pk_bf16_f32 v61, v4, v5
	s_waitcnt vmcnt(4)
	v_lshlrev_b32_e32 v4, 16, v8
	v_and_b32_e32 v5, 0xffff0000, v8
	v_pk_mul_f32 v[4:5], v[74:75], v[4:5] op_sel_hi:[0,1]
	v_cvt_pk_bf16_f32 v62, v4, v5
	v_lshlrev_b32_e32 v4, 16, v9
	v_and_b32_e32 v5, 0xffff0000, v9
	v_pk_mul_f32 v[4:5], v[74:75], v[4:5] op_sel_hi:[0,1]
	v_cvt_pk_bf16_f32 v63, v4, v5
	v_lshlrev_b32_e32 v4, 16, v10
	v_and_b32_e32 v5, 0xffff0000, v10
	v_pk_mul_f32 v[4:5], v[74:75], v[4:5] op_sel_hi:[0,1]
	v_cvt_pk_bf16_f32 v64, v4, v5
	v_lshlrev_b32_e32 v4, 16, v11
	v_and_b32_e32 v5, 0xffff0000, v11
	v_pk_mul_f32 v[12:13], v[72:73], v[12:13] op_sel_hi:[0,1]
	v_pk_mul_f32 v[4:5], v[74:75], v[4:5] op_sel_hi:[0,1]
	v_lshlrev_b32_e32 v6, 5, v24
	v_cvt_pk_bf16_f32 v58, v12, v13
	v_cvt_pk_bf16_f32 v65, v4, v5
	v_lshl_add_u64 v[4:5], s[10:11], 0, v[2:3]
	v_ashrrev_i32_e32 v7, 31, v6
	ds_write_b128 v82, v[58:61] offset:32768
	ds_write_b128 v83, v[62:65] offset:32768
	v_lshl_add_u64 v[4:5], v[6:7], 1, v[4:5]
	v_lshlrev_b32_e32 v2, 1, v21
	s_waitcnt lgkmcnt(0)
	s_barrier
	v_lshl_add_u64 v[4:5], v[4:5], 0, v[2:3]
	v_lshlrev_b32_e32 v2, 5, v20
	v_and_b32_e32 v2, 0x400, v2
	v_lshl_add_u64 v[78:79], v[4:5], 0, v[2:3]
	v_mov_b32_e32 v2, v3
	v_mov_b32_e32 v4, v3
	v_mov_b32_e32 v5, v3
	v_mov_b32_e32 v6, v3
	v_mov_b32_e32 v7, v3
	v_mov_b32_e32 v8, v3
	v_mov_b32_e32 v9, v3
	v_mov_b32_e32 v10, v3
	v_mov_b32_e32 v11, v3
	v_mov_b32_e32 v12, v3
	v_mov_b32_e32 v13, v3
	v_mov_b32_e32 v20, v3
	v_mov_b32_e32 v21, v3
	v_mov_b32_e32 v24, v3
	s_branch .LBB0_1870
.LBB0_1868:
	ds_write_b128 v82, v[34:37]
	ds_write_b128 v83, v[38:41]
	s_mov_b64 exec, s[36:37]
	v_lshlrev_b32_e32 v86, 16, v58
	v_and_b32_e32 v87, 0xffff0000, v58
	v_pk_mul_f32 v[86:87], v[72:73], v[86:87]
	v_cvt_pk_bf16_f32 v58, v86, v87
	v_lshlrev_b32_e32 v86, 16, v59
	v_and_b32_e32 v87, 0xffff0000, v59
	v_pk_mul_f32 v[86:87], v[72:73], v[86:87]
	s_nop 0
	v_cvt_pk_bf16_f32 v59, v86, v87
	v_lshlrev_b32_e32 v86, 16, v60
	v_and_b32_e32 v87, 0xffff0000, v60
	v_pk_mul_f32 v[86:87], v[72:73], v[86:87]
	s_nop 0
	v_cvt_pk_bf16_f32 v60, v86, v87
	v_lshlrev_b32_e32 v86, 16, v61
	v_and_b32_e32 v87, 0xffff0000, v61
	v_pk_mul_f32 v[86:87], v[72:73], v[86:87]
	s_nop 0
	v_cvt_pk_bf16_f32 v61, v86, v87
	v_lshlrev_b32_e32 v86, 16, v62
	v_and_b32_e32 v87, 0xffff0000, v62
	v_pk_mul_f32 v[86:87], v[74:75], v[86:87]
	s_nop 0
	v_cvt_pk_bf16_f32 v62, v86, v87
	v_lshlrev_b32_e32 v86, 16, v63
	v_and_b32_e32 v87, 0xffff0000, v63
	v_pk_mul_f32 v[86:87], v[74:75], v[86:87]
	s_nop 0
	v_cvt_pk_bf16_f32 v63, v86, v87
	v_lshlrev_b32_e32 v86, 16, v64
	v_and_b32_e32 v87, 0xffff0000, v64
	v_pk_mul_f32 v[86:87], v[74:75], v[86:87]
	s_nop 0
	v_cvt_pk_bf16_f32 v64, v86, v87
	v_lshlrev_b32_e32 v86, 16, v65
	v_and_b32_e32 v87, 0xffff0000, v65
	v_pk_mul_f32 v[86:87], v[74:75], v[86:87]
	s_nop 0
	v_cvt_pk_bf16_f32 v65, v86, v87
	ds_write_b128 v82, v[58:61] offset:32768
	ds_write_b128 v83, v[62:65] offset:32768
	s_mov_b64 exec, -1

.LBB0_1870:
	s_add_i32 s20, s21, 2
	s_cmp_lt_u32 s21, 34
	s_cselect_b64 s[12:13], -1, 0
	s_cmp_gt_u32 s21, 33
	s_cselect_b64 s[10:11], -1, 0
	s_and_b64 vcc, exec, s[10:11]
	v_lshlrev_b32_e32 v86, 1, v68
	s_cbranch_vccnz .LBB0_1872
	s_add_i32 s4, s18, 1
	s_cmp_lg_u32 s21, 0
	s_cselect_b32 s4, s4, 1
	s_and_b64 s[14:15], s[0:1], exec
	s_cselect_b32 s4, s20, s4
	s_lshl_b32 s4, s4, 6
	v_lshl_add_u64 v[34:35], s[4:5], 0, v[66:67]
	v_lshlrev_b64 v[58:59], 10, v[34:35]
	v_lshl_add_u64 v[34:35], v[70:71], 0, s[4:5]
	v_lshlrev_b64 v[62:63], 10, v[34:35]
	v_or_b32_e32 v58, v58, v86
	v_or_b32_e32 v62, v62, v86
	v_lshl_add_u64 v[60:61], s[6:7], 0, v[58:59]
	v_lshl_add_u64 v[64:65], s[6:7], 0, v[62:63]
	v_lshl_add_u64 v[88:89], s[8:9], 0, v[58:59]
	global_load_dwordx4 v[34:37], v[60:61], off
	global_load_dwordx4 v[38:41], v[64:65], off
	v_lshl_add_u64 v[90:91], s[8:9], 0, v[62:63]
	s_mov_b64 exec, s[36:37]
	global_load_dwordx4 v[58:61], v[88:89], off
	s_mov_b64 exec, -1
	s_mov_b64 exec, s[36:37]
	global_load_dwordx4 v[62:65], v[90:91], off
	s_mov_b64 exec, -1

.LBB0_1884:
	s_waitcnt vmcnt(1)
	ds_write_b128 v82, v[42:45] offset:16384
	ds_write_b128 v83, v[46:49] offset:16384
	s_mov_b64 exec, s[36:37]
	v_lshlrev_b32_e32 v88, 16, v50
	v_and_b32_e32 v89, 0xffff0000, v50
	v_pk_mul_f32 v[88:89], v[72:73], v[88:89]
	v_cvt_pk_bf16_f32 v50, v88, v89
	v_lshlrev_b32_e32 v88, 16, v51
	v_and_b32_e32 v89, 0xffff0000, v51
	v_pk_mul_f32 v[88:89], v[72:73], v[88:89]
	s_cmp_gt_u32 s21, 32
	v_cvt_pk_bf16_f32 v51, v88, v89
	v_lshlrev_b32_e32 v88, 16, v52
	v_and_b32_e32 v89, 0xffff0000, v52
	v_pk_mul_f32 v[88:89], v[72:73], v[88:89]
	s_nop 0
	v_cvt_pk_bf16_f32 v52, v88, v89
	v_lshlrev_b32_e32 v88, 16, v53
	v_and_b32_e32 v89, 0xffff0000, v53
	v_pk_mul_f32 v[88:89], v[72:73], v[88:89]
	s_nop 0
	v_cvt_pk_bf16_f32 v53, v88, v89
	s_waitcnt vmcnt(0)
	v_lshlrev_b32_e32 v88, 16, v54
	v_and_b32_e32 v89, 0xffff0000, v54
	v_pk_mul_f32 v[88:89], v[74:75], v[88:89]
	s_nop 0
	v_cvt_pk_bf16_f32 v54, v88, v89
	v_lshlrev_b32_e32 v88, 16, v55
	v_and_b32_e32 v89, 0xffff0000, v55
	v_pk_mul_f32 v[88:89], v[74:75], v[88:89]
	s_nop 0
	v_cvt_pk_bf16_f32 v55, v88, v89
	v_lshlrev_b32_e32 v88, 16, v56
	v_and_b32_e32 v89, 0xffff0000, v56
	v_pk_mul_f32 v[88:89], v[74:75], v[88:89]
	s_nop 0
	v_cvt_pk_bf16_f32 v56, v88, v89
	v_lshlrev_b32_e32 v88, 16, v57
	v_and_b32_e32 v89, 0xffff0000, v57
	v_pk_mul_f32 v[88:89], v[74:75], v[88:89]
	s_nop 0
	v_cvt_pk_bf16_f32 v57, v88, v89
	ds_write_b128 v82, v[50:53] offset:49152
	ds_write_b128 v83, v[54:57] offset:49152
	s_mov_b64 exec, -1
	s_waitcnt lgkmcnt(0)
	s_barrier
	s_cbranch_scc1 .LBB0_1886
	s_add_i32 s4, s21, 3
	s_cmp_lg_u32 s21, 0
	s_cselect_b32 s21, s18, 0
	s_and_b64 s[16:17], s[0:1], exec
	s_cselect_b32 s4, s4, s21
	s_lshl_b32 s4, s4, 6
	v_lshl_add_u64 v[42:43], s[4:5], 0, v[66:67]
	v_lshlrev_b64 v[50:51], 10, v[42:43]
	v_lshl_add_u64 v[42:43], v[70:71], 0, s[4:5]
	v_lshlrev_b64 v[54:55], 10, v[42:43]
	v_or_b32_e32 v50, v50, v86
	v_or_b32_e32 v54, v54, v86
	v_lshl_add_u64 v[52:53], s[6:7], 0, v[50:51]
	v_lshl_add_u64 v[56:57], s[6:7], 0, v[54:55]
	v_lshl_add_u64 v[86:87], s[8:9], 0, v[50:51]
	global_load_dwordx4 v[42:45], v[52:53], off
	global_load_dwordx4 v[46:49], v[56:57], off
	v_lshl_add_u64 v[88:89], s[8:9], 0, v[54:55]
	s_mov_b64 exec, s[36:37]
	global_load_dwordx4 v[50:53], v[86:87], off
	s_mov_b64 exec, -1
	s_mov_b64 exec, s[36:37]
	global_load_dwordx4 v[54:57], v[88:89], off
	s_mov_b64 exec, -1
